# wout_v89 + GDN prep log-decay prefix scan with DPP row shifts instead of six ds_bpermute round trips
# baseline (speedup 1.0000x reference)
.LBB0_674:
	s_or_b64 exec, exec, s[4:5]
	s_nop 4
	v_add_f32_dpp v37, v37, v37 row_shr:1 row_mask:0xf bank_mask:0xf
	s_nop 1
	v_add_f32_dpp v37, v37, v37 row_shr:2 row_mask:0xf bank_mask:0xf
	s_nop 1
	v_add_f32_dpp v37, v37, v37 row_shr:4 row_mask:0xf bank_mask:0xf
	s_nop 1
	v_add_f32_dpp v37, v37, v37 row_shr:8 row_mask:0xf bank_mask:0xf
	s_nop 1
	v_add_f32_dpp v37, v37, v37 row_bcast:15 row_mask:0xa bank_mask:0xf
	s_nop 1
	v_add_f32_dpp v37, v37, v37 row_bcast:31 row_mask:0xc bank_mask:0xf
	s_nop 1
	v_lshlrev_b32_e32 v38, 2, v96
	ds_write2st64_b32 v38, v37, v36 offset0:240 offset1:241

.LBB0_1156:
	v_xor_b32_e32 v3, v3, v2
	v_lshlrev_b32_e32 v2, 6, v2
	v_and_b32_e32 v168, 0x1000, v2
	v_and_b32_e32 v166, 0x3c0, v2
	v_and_b32_e32 v167, 0xffffe000, v2
	v_lshlrev_b32_e32 v2, 1, v3
	v_and_b32_e32 v128, 48, v2
	s_and_b32 s24, s57, 0x380
	v_lshl_add_u64 v[0:1], v[0:1], 0, v[254:255]
	v_lshl_add_u64 v[134:135], s[20:21], 0, v[0:1]
	v_add_u32_e32 v0, s24, v163
	v_ashrrev_i32_e32 v1, 31, v0
	v_lshlrev_b64 v[0:1], 6, v[0:1]
	v_or_b32_e32 v0, v0, v128
	v_lshl_add_u64 v[136:137], s[20:21], 0, v[0:1]
	v_mov_b32_e32 v0, 0
	v_and_b32_e32 v133, 48, v3
	s_mov_b32 s46, 1
	s_mov_b64 s[44:45], 0
	v_mov_b32_e32 v1, v0
	v_mov_b32_e32 v2, v0
	v_mov_b32_e32 v3, v0
	v_mov_b32_e32 v4, v0
	v_mov_b32_e32 v5, v0
	v_mov_b32_e32 v6, v0
	v_mov_b32_e32 v7, v0
	v_mov_b32_e32 v8, v0
	v_mov_b32_e32 v9, v0
	v_mov_b32_e32 v10, v0
	v_mov_b32_e32 v11, v0
	v_mov_b32_e32 v12, v0
	v_mov_b32_e32 v13, v0
	v_mov_b32_e32 v14, v0
	v_mov_b32_e32 v15, v0
	v_mov_b32_e32 v16, v0
	v_mov_b32_e32 v17, v0
	v_mov_b32_e32 v18, v0
	v_mov_b32_e32 v19, v0
	v_mov_b32_e32 v20, v0
	v_mov_b32_e32 v21, v0
	v_mov_b32_e32 v22, v0
	v_mov_b32_e32 v23, v0
	v_mov_b32_e32 v24, v0
	v_mov_b32_e32 v25, v0
	v_mov_b32_e32 v26, v0
	v_mov_b32_e32 v27, v0
	v_mov_b32_e32 v28, v0
	v_mov_b32_e32 v29, v0
	v_mov_b32_e32 v30, v0
	v_mov_b32_e32 v31, v0
	v_mov_b32_e32 v32, v0
	v_mov_b32_e32 v33, v0
	v_mov_b32_e32 v34, v0
	v_mov_b32_e32 v35, v0
	v_mov_b32_e32 v36, v0
	v_mov_b32_e32 v37, v0
	v_mov_b32_e32 v38, v0
	v_mov_b32_e32 v39, v0
	v_mov_b32_e32 v40, v0
	v_mov_b32_e32 v41, v0
	v_mov_b32_e32 v42, v0
	v_mov_b32_e32 v43, v0
	v_mov_b32_e32 v44, v0
	v_mov_b32_e32 v45, v0
	v_mov_b32_e32 v46, v0
	v_mov_b32_e32 v47, v0
	v_mov_b32_e32 v48, v0
	v_mov_b32_e32 v49, v0
	v_mov_b32_e32 v50, v0
	v_mov_b32_e32 v51, v0
	v_mov_b32_e32 v52, v0
	v_mov_b32_e32 v53, v0
	v_mov_b32_e32 v54, v0
	v_mov_b32_e32 v55, v0
	v_mov_b32_e32 v56, v0
	v_mov_b32_e32 v57, v0
	v_mov_b32_e32 v58, v0
	v_mov_b32_e32 v59, v0
	v_mov_b32_e32 v60, v0
	v_mov_b32_e32 v61, v0
	v_mov_b32_e32 v62, v0
	v_mov_b32_e32 v63, v0
	v_mov_b32_e32 v64, v0
	v_mov_b32_e32 v65, v0
	v_mov_b32_e32 v66, v0
	v_mov_b32_e32 v67, v0
	v_mov_b32_e32 v68, v0
	v_mov_b32_e32 v69, v0
	v_mov_b32_e32 v70, v0
	v_mov_b32_e32 v71, v0
	v_mov_b32_e32 v72, v0
	v_mov_b32_e32 v73, v0
	v_mov_b32_e32 v74, v0
	v_mov_b32_e32 v75, v0
	v_mov_b32_e32 v76, v0
	v_mov_b32_e32 v77, v0
	v_mov_b32_e32 v78, v0
	v_mov_b32_e32 v79, v0
	v_mov_b32_e32 v80, v0
	v_mov_b32_e32 v81, v0
	v_mov_b32_e32 v82, v0
	v_mov_b32_e32 v83, v0
	v_mov_b32_e32 v84, v0
	v_mov_b32_e32 v85, v0
	v_mov_b32_e32 v86, v0
	v_mov_b32_e32 v87, v0
	v_mov_b32_e32 v88, v0
	v_mov_b32_e32 v89, v0
	v_mov_b32_e32 v90, v0
	v_mov_b32_e32 v91, v0
	v_mov_b32_e32 v92, v0
	v_mov_b32_e32 v93, v0
	v_mov_b32_e32 v94, v0
	v_mov_b32_e32 v95, v0
	v_mov_b32_e32 v96, v0
	v_mov_b32_e32 v97, v0
	v_mov_b32_e32 v98, v0
	v_mov_b32_e32 v99, v0
	v_mov_b32_e32 v100, v0
	v_mov_b32_e32 v101, v0
	v_mov_b32_e32 v102, v0
	v_mov_b32_e32 v103, v0
	v_mov_b32_e32 v104, v0
	v_mov_b32_e32 v105, v0
	v_mov_b32_e32 v106, v0
	v_mov_b32_e32 v107, v0
	v_mov_b32_e32 v108, v0
	v_mov_b32_e32 v109, v0
	v_mov_b32_e32 v110, v0
	v_mov_b32_e32 v111, v0
	v_mov_b32_e32 v112, v0
	v_mov_b32_e32 v113, v0
	v_mov_b32_e32 v114, v0
	v_mov_b32_e32 v115, v0
	v_mov_b32_e32 v116, v0
	v_mov_b32_e32 v117, v0
	v_mov_b32_e32 v118, v0
	v_mov_b32_e32 v119, v0
	v_mov_b32_e32 v120, v0
	v_mov_b32_e32 v121, v0
	v_mov_b32_e32 v122, v0
	v_mov_b32_e32 v123, v0
	v_mov_b32_e32 v124, v0
	v_mov_b32_e32 v125, v0
	v_mov_b32_e32 v126, v0
	v_mov_b32_e32 v127, v0
	s_waitcnt vmcnt(0) lgkmcnt(0)
	s_barrier
.LBB0_1157:
	s_lshl_b64 s[98:99], s[44:45], 10
	s_bitcmp1_b32 s46, 0
	s_cselect_b32 s24, 0x6000, 0
	v_add_u32_e32 v128, s24, v165
	v_lshl_add_u64 v[170:171], v[134:135], 0, s[98:99]
	v_readfirstlane_b32 s24, v128
	v_add_u32_e32 v169, 0x1000, v128
	v_lshl_add_u64 v[172:173], v[170:171], 0, s[100:101]
	s_mov_b32 m0, s24
	v_readfirstlane_b32 s24, v169
	v_add_u32_e32 v169, 0x2000, v128
	global_load_lds_dwordx4 v[172:173], off
	v_lshl_add_u64 v[172:173], v[170:171], 0, s[34:35]
	s_mov_b32 m0, s24
	v_readfirstlane_b32 s24, v169
	v_add_u32_e32 v169, 0x3000, v128
	global_load_lds_dwordx4 v[172:173], off
	v_lshl_add_u64 v[172:173], v[170:171], 0, s[36:37]
	s_mov_b32 m0, s24
	v_readfirstlane_b32 s24, v169
	global_load_lds_dwordx4 v[172:173], off
	v_lshl_add_u64 v[170:171], v[170:171], 0, s[38:39]
	s_mov_b32 m0, s24
	v_add_u32_e32 v169, 0x4000, v128
	global_load_lds_dwordx4 v[170:171], off
	v_lshl_add_u64 v[170:171], v[136:137], 0, s[98:99]
	v_readfirstlane_b32 s24, v169
	v_add_u32_e32 v128, 0x5000, v128
	v_lshl_add_u64 v[172:173], v[170:171], 0, s[40:41]
	s_mov_b32 m0, s24
	v_readfirstlane_b32 s24, v128
	global_load_lds_dwordx4 v[172:173], off
	v_lshl_add_u64 v[170:171], v[170:171], 0, s[42:43]
	s_mov_b32 m0, s24
	s_nop 0
	global_load_lds_dwordx4 v[170:171], off
	s_cselect_b32 s24, 0, 0x6000
	v_or_b32_e32 v128, s24, v168
	v_add3_u32 v128, v128, v166, v133
	ds_read_b128 v[170:173], v128 offset:16384
	ds_read_b128 v[174:177], v128 offset:17408
	ds_read_b128 v[184:187], v128 offset:18432
	ds_read_b128 v[188:191], v128 offset:19456
	v_add_u32_e32 v128, s24, v167
	v_add3_u32 v128, v128, v166, v133
	ds_read_b128 v[192:195], v128
	ds_read_b128 v[196:199], v128 offset:1024
	ds_read_b128 v[200:203], v128 offset:2048
	ds_read_b128 v[204:207], v128 offset:3072
	ds_read_b128 v[208:211], v128 offset:4096
	ds_read_b128 v[212:215], v128 offset:5120
	ds_read_b128 v[216:219], v128 offset:6144
	ds_read_b128 v[220:223], v128 offset:7168
	s_setprio 1
	s_waitcnt lgkmcnt(0)
	v_mfma_f32_16x16x32_bf16 v[124:127], v[170:173], v[192:195], v[124:127]
	v_mfma_f32_16x16x32_bf16 v[120:123], v[174:177], v[192:195], v[120:123]
	v_mfma_f32_16x16x32_bf16 v[116:119], v[184:187], v[192:195], v[116:119]
	v_mfma_f32_16x16x32_bf16 v[112:115], v[188:191], v[192:195], v[112:115]
	v_mfma_f32_16x16x32_bf16 v[108:111], v[170:173], v[196:199], v[108:111]
	v_mfma_f32_16x16x32_bf16 v[104:107], v[174:177], v[196:199], v[104:107]
	v_mfma_f32_16x16x32_bf16 v[100:103], v[184:187], v[196:199], v[100:103]
	v_mfma_f32_16x16x32_bf16 v[96:99], v[188:191], v[196:199], v[96:99]
	v_mfma_f32_16x16x32_bf16 v[92:95], v[170:173], v[200:203], v[92:95]
	v_mfma_f32_16x16x32_bf16 v[88:91], v[174:177], v[200:203], v[88:91]
	v_mfma_f32_16x16x32_bf16 v[84:87], v[184:187], v[200:203], v[84:87]
	v_mfma_f32_16x16x32_bf16 v[80:83], v[188:191], v[200:203], v[80:83]
	v_mfma_f32_16x16x32_bf16 v[76:79], v[170:173], v[204:207], v[76:79]
	v_mfma_f32_16x16x32_bf16 v[72:75], v[174:177], v[204:207], v[72:75]
	v_mfma_f32_16x16x32_bf16 v[68:71], v[184:187], v[204:207], v[68:71]
	v_mfma_f32_16x16x32_bf16 v[64:67], v[188:191], v[204:207], v[64:67]
	v_mfma_f32_16x16x32_bf16 v[60:63], v[170:173], v[208:211], v[60:63]
	v_mfma_f32_16x16x32_bf16 v[56:59], v[174:177], v[208:211], v[56:59]
	v_mfma_f32_16x16x32_bf16 v[52:55], v[184:187], v[208:211], v[52:55]
	v_mfma_f32_16x16x32_bf16 v[48:51], v[188:191], v[208:211], v[48:51]
	v_mfma_f32_16x16x32_bf16 v[44:47], v[170:173], v[212:215], v[44:47]
	v_mfma_f32_16x16x32_bf16 v[40:43], v[174:177], v[212:215], v[40:43]
	v_mfma_f32_16x16x32_bf16 v[36:39], v[184:187], v[212:215], v[36:39]
	v_mfma_f32_16x16x32_bf16 v[32:35], v[188:191], v[212:215], v[32:35]
	v_mfma_f32_16x16x32_bf16 v[28:31], v[170:173], v[216:219], v[28:31]
	v_mfma_f32_16x16x32_bf16 v[24:27], v[174:177], v[216:219], v[24:27]
	v_mfma_f32_16x16x32_bf16 v[20:23], v[184:187], v[216:219], v[20:23]
	v_mfma_f32_16x16x32_bf16 v[16:19], v[188:191], v[216:219], v[16:19]
	v_mfma_f32_16x16x32_bf16 v[12:15], v[170:173], v[220:223], v[12:15]
	v_mfma_f32_16x16x32_bf16 v[8:11], v[174:177], v[220:223], v[8:11]
	v_mfma_f32_16x16x32_bf16 v[4:7], v[184:187], v[220:223], v[4:7]
	v_mfma_f32_16x16x32_bf16 v[0:3], v[188:191], v[220:223], v[0:3]
	s_setprio 0
	s_add_u32 s44, s44, 64
	s_addc_u32 s45, s45, 0
	s_add_i32 s46, s46, 1
	s_cmpk_eq_i32 s44, 0x7c0
	s_waitcnt vmcnt(0)
	s_barrier
	s_cbranch_scc0 .LBB0_1157
	s_add_i32 s88, s88, s89
	s_cmp_ge_i32 s88, s56
	s_cselect_b64 s[44:45], -1, 0
	s_cmp_lt_i32 s88, s56
	v_add3_u32 v128, v168, v166, v133
	ds_read_b128 v[134:137], v128 offset:40960
	ds_read_b128 v[168:171], v128 offset:41984
	ds_read_b128 v[172:175], v128 offset:43008
	ds_read_b128 v[176:179], v128 offset:44032
	v_add3_u32 v128, v167, v166, v133
	ds_read_b128 v[184:187], v128 offset:24576
	ds_read_b128 v[188:191], v128 offset:25600
	ds_read_b128 v[192:195], v128 offset:26624
	ds_read_b128 v[196:199], v128 offset:27648
	ds_read_b128 v[200:203], v128 offset:28672
	ds_read_b128 v[204:207], v128 offset:29696
	ds_read_b128 v[208:211], v128 offset:30720
	ds_read_b128 v[212:215], v128 offset:31744
	s_setprio 1
	s_waitcnt lgkmcnt(7)
	v_mfma_f32_16x16x32_bf16 v[124:127], v[134:137], v[184:187], v[124:127]
	v_mfma_f32_16x16x32_bf16 v[120:123], v[168:171], v[184:187], v[120:123]
	v_mfma_f32_16x16x32_bf16 v[116:119], v[172:175], v[184:187], v[116:119]
	v_mfma_f32_16x16x32_bf16 v[112:115], v[176:179], v[184:187], v[112:115]
	s_waitcnt lgkmcnt(6)
	v_mfma_f32_16x16x32_bf16 v[108:111], v[134:137], v[188:191], v[108:111]
	v_mfma_f32_16x16x32_bf16 v[104:107], v[168:171], v[188:191], v[104:107]
	v_mfma_f32_16x16x32_bf16 v[100:103], v[172:175], v[188:191], v[100:103]
	v_mfma_f32_16x16x32_bf16 v[96:99], v[176:179], v[188:191], v[96:99]
	s_waitcnt lgkmcnt(5)
	v_mfma_f32_16x16x32_bf16 v[92:95], v[134:137], v[192:195], v[92:95]
	v_mfma_f32_16x16x32_bf16 v[88:91], v[168:171], v[192:195], v[88:91]
	v_mfma_f32_16x16x32_bf16 v[84:87], v[172:175], v[192:195], v[84:87]
	v_mfma_f32_16x16x32_bf16 v[80:83], v[176:179], v[192:195], v[80:83]
	s_waitcnt lgkmcnt(4)
	v_mfma_f32_16x16x32_bf16 v[76:79], v[134:137], v[196:199], v[76:79]
	v_mfma_f32_16x16x32_bf16 v[72:75], v[168:171], v[196:199], v[72:75]
	v_mfma_f32_16x16x32_bf16 v[68:71], v[172:175], v[196:199], v[68:71]
	v_mfma_f32_16x16x32_bf16 v[64:67], v[176:179], v[196:199], v[64:67]
	s_waitcnt lgkmcnt(3)
	v_mfma_f32_16x16x32_bf16 v[60:63], v[134:137], v[200:203], v[60:63]
	v_mfma_f32_16x16x32_bf16 v[56:59], v[168:171], v[200:203], v[56:59]
	v_mfma_f32_16x16x32_bf16 v[52:55], v[172:175], v[200:203], v[52:55]
	v_mfma_f32_16x16x32_bf16 v[48:51], v[176:179], v[200:203], v[48:51]
	s_waitcnt lgkmcnt(2)
	v_mfma_f32_16x16x32_bf16 v[44:47], v[134:137], v[204:207], v[44:47]
	v_mfma_f32_16x16x32_bf16 v[40:43], v[168:171], v[204:207], v[40:43]
	v_mfma_f32_16x16x32_bf16 v[36:39], v[172:175], v[204:207], v[36:39]
	v_mfma_f32_16x16x32_bf16 v[32:35], v[176:179], v[204:207], v[32:35]
	s_waitcnt lgkmcnt(1)
	v_mfma_f32_16x16x32_bf16 v[28:31], v[134:137], v[208:211], v[28:31]
	v_mfma_f32_16x16x32_bf16 v[24:27], v[168:171], v[208:211], v[24:27]
	v_mfma_f32_16x16x32_bf16 v[20:23], v[172:175], v[208:211], v[20:23]
	v_mfma_f32_16x16x32_bf16 v[16:19], v[176:179], v[208:211], v[16:19]
	s_waitcnt lgkmcnt(0)
	v_mfma_f32_16x16x32_bf16 v[12:15], v[134:137], v[212:215], v[12:15]
	v_mfma_f32_16x16x32_bf16 v[8:11], v[168:171], v[212:215], v[8:11]
	v_mfma_f32_16x16x32_bf16 v[4:7], v[172:175], v[212:215], v[4:7]
	v_mfma_f32_16x16x32_bf16 v[0:3], v[176:179], v[212:215], v[0:3]
	s_setprio 0
	s_barrier
	s_cbranch_scc0 .LBB0_1160
	s_lshr_b32 s24, s88, 3
	s_mul_i32 s24, s24, s29
	s_add_i32 s24, s24, s28
	s_lshl_b32 s25, s88, 7
	s_and_b32 s25, s25, 0x380
	v_lshl_add_u32 v134, s24, 8, v245
	v_ashrrev_i32_e32 v135, 31, v134
	v_add_u32_e32 v136, s25, v163
	v_lshlrev_b64 v[134:135], 13, v[134:135]
	v_ashrrev_i32_e32 v137, 31, v136
	v_lshl_add_u64 v[134:135], s[20:21], 0, v[134:135]
	v_mov_b32_e32 v133, v129
	v_lshlrev_b64 v[136:137], 6, v[136:137]
	v_readfirstlane_b32 s24, v165
	v_lshl_add_u64 v[134:135], v[134:135], 0, v[254:255]
	v_lshl_add_u64 v[136:137], s[8:9], 0, v[136:137]
	s_mov_b32 m0, s24
	v_readfirstlane_b32 s24, v164
	v_lshl_add_u64 v[132:133], v[136:137], 0, v[132:133]
	global_load_lds_dwordx4 v[134:135], off
	v_lshl_add_u64 v[136:137], v[134:135], 0, s[12:13]
	s_mov_b32 m0, s24
	v_readfirstlane_b32 s24, v162
	global_load_lds_dwordx4 v[136:137], off
	v_lshl_add_u64 v[136:137], v[134:135], 0, s[14:15]
	s_mov_b32 m0, s24
	v_readfirstlane_b32 s24, v161
	global_load_lds_dwordx4 v[136:137], off
	v_lshl_add_u64 v[134:135], v[134:135], 0, s[16:17]
	s_mov_b32 m0, s24
	v_readfirstlane_b32 s24, v160
	global_load_lds_dwordx4 v[134:135], off
	s_mov_b32 m0, s24
	v_readfirstlane_b32 s24, v159
	global_load_lds_dwordx4 v[132:133], off
	v_lshl_add_u64 v[132:133], v[132:133], 0, s[30:31]
	s_mov_b32 m0, s24
	s_nop 0
	global_load_lds_dwordx4 v[132:133], off
